# k17 plus: leading half runs its first two SwiGLU epilogue row groups before the alignment barrier (while the trailing half finishes its last MFMA block)
# speedup vs baseline: 1.0067x; 1.0017x over previous
; __device__ __forceinline__ float rstd_of(float ss, float inv_n) { return __builtin_amdgcn_rsqf(ss * inv_n + 1e-6f); }
; __device__ __forceinline__ float sigmoid_f(float v) { return __builtin_amdgcn_rcpf(1.0f + __builtin_amdgcn_exp2f(-1.4426950408889634f * v)); }
; __device__ __forceinline__ u32x4 pack8(const f32x4 a, const f32x4 b) { u32x4 w; w.x = cvt_pk_bf16(a[0], a[1]); w.y = cvt_pk_bf16(a[2], a[3]); w.z = cvt_pk_bf16(b[0], b[1]); w.w = cvt_pk_bf16(b[2], b[3]); return w; }
; #define PG8_BAR __builtin_amdgcn_s_barrier()
;     __device__ __forceinline__ void operator()(f32x4 (&acc)[2][2][4][2], const Unit& u_, int wr, int wc, int fr, int fq) const {
;     ...
;         const int row0 = u.pm * BM + wr * 64 + fr, col0 = u.pn * HALF + wc * 32 + 8 * fq;
; #pragma unroll
;         for (int ai = 0; ai < 2; ++ai)
; #pragma unroll
;             for (int m = 0; m < 4; ++m) {
;                 const int row = row0 + ai * HALF + m * 16; const float r = rstd_of(sl[u.par * 256 + ai * HALF + wr * 64 + m * 16 + fr], 1.0f / 2048.0f) * ascale;
;                 f32x4 o[2];
; #pragma unroll
;                 for (int n = 0; n < 2; ++n) { const f32x4 g = acc[ai][0][m][n] * r, uu = acc[ai][1][m][n] * r;
; #pragma unroll
;                     for (int e = 0; e < 4; ++e) o[n][e] = g[e] * uu[e] * sigmoid_f(g[e]); }
;                 if constexpr (F8OUT) {
;                     typedef unsigned u32x2 __attribute__((ext_vector_type(2))); u32x2 w8; w8.x = pack4_fp8(o[0][0] * F8_ACT_SCALE, o[0][1] * F8_ACT_SCALE, o[0][2] * F8_ACT_SCALE, o[0][3] * F8_ACT_SCALE);
;                     w8.y = pack4_fp8(o[1][0] * F8_ACT_SCALE, o[1][1] * F8_ACT_SCALE, o[1][2] * F8_ACT_SCALE, o[1][3] * F8_ACT_SCALE);
;                     *(u32x2*)((unsigned char*)O + (((size_t)u.pm * (ldo / 128) + (col0 >> 7)) * BM + (ai * HALF + wr * 64 + m * 16 + fr)) * 128 + (col0 & 127)) = w8;
;                 } else
;                 *(u32x4*)(O + (((size_t)u.pm * (ldo / 64) + (col0 >> 6)) * BM + (ai * HALF + wr * 64 + m * 16 + fr)) * 64 + (col0 & 63)) = pack8(o[0], o[1]);
; template <class Epi, class Sched, bool ALIGN_EPI = false, bool SP2 = false, bool ABLK = false, bool F8 = false>
; __device__ __forceinline__ void gemm_phase(PG8_LAS unsigned char* lds, const Gemm g, const Sched& S, const Epi& E, const int wave_s) {
;     ...
;         if constexpr (ALIGN_EPI) { if (wr == 0) PG8_BAR; }
.LBB0_228:
	v_lshl_add_u32 v166, s76, 10, v162
	ds_read_b32 v172, v166
	ds_read_b32 v173, v166 offset:64
	ds_read_b32 v174, v166 offset:128
	ds_read_b32 v175, v166 offset:192
	ds_read_b32 v176, v166 offset:512
	ds_read_b32 v177, v166 offset:576
	ds_read_b32 v178, v166 offset:640
	ds_read_b32 v179, v166 offset:704
	v_lshl_add_u32 v167, s56, 7, v161
	s_andn2_b64 vcc, exec, s[6:7]
	s_mov_b64 s[6:7], -1
	v_ashrrev_i32_e32 v168, 6, v167
	v_ashrrev_i32_e32 v169, 31, v168
	v_mad_i64_i32 v[180:181], s[8:9], s54, v165, v[168:169]
	v_mov_b32_e32 v170, v152
	v_mov_b32_e32 v171, v129
	v_lshlrev_b64 v[180:181], 15, v[180:181]
	v_mov_b32_e32 v182, 1.0
	v_lshl_add_u64 v[180:181], s[34:35], 0, v[180:181]
	v_lshl_add_u64 v[180:181], v[180:181], 0, v[170:171]
	s_waitcnt lgkmcnt(0)
	v_fmamk_f32 v184, v172, 0x3a000000, v164
	v_rsq_f32_e32 v184, v184
	v_lshl_add_u64 v[202:203], v[180:181], 0, v[130:131]
	v_mul_f32_e32 v186, 0xbfb8aa3b, v184
	v_mul_f32_e32 v188, v184, v184
	v_pk_mul_f32 v[190:191], v[124:125], v[186:187] op_sel_hi:[1,0]
	v_pk_mul_f32 v[192:193], v[126:127], v[186:187] op_sel_hi:[1,0]
	v_pk_mul_f32 v[124:125], v[124:125], v[120:121]
	v_exp_f32_e32 v190, v190
	v_exp_f32_e32 v191, v191
	v_exp_f32_e32 v192, v192
	v_exp_f32_e32 v193, v193
	v_pk_mul_f32 v[126:127], v[126:127], v[122:123]
	v_pk_add_f32 v[190:191], v[190:191], v[182:183] op_sel_hi:[1,0]
	v_pk_add_f32 v[192:193], v[192:193], v[182:183] op_sel_hi:[1,0]
	v_pk_mul_f32 v[124:125], v[124:125], v[188:189] op_sel_hi:[1,0]
	v_rcp_f32_e32 v190, v190
	v_rcp_f32_e32 v191, v191
	v_rcp_f32_e32 v192, v192
	v_rcp_f32_e32 v193, v193
	v_pk_mul_f32 v[126:127], v[126:127], v[188:189] op_sel_hi:[1,0]
	v_pk_mul_f32 v[124:125], v[124:125], v[190:191]
	v_pk_mul_f32 v[126:127], v[126:127], v[192:193]
	v_pk_mul_f32 v[190:191], v[116:117], v[186:187] op_sel_hi:[1,0]
	v_pk_mul_f32 v[192:193], v[118:119], v[186:187] op_sel_hi:[1,0]
	v_pk_mul_f32 v[116:117], v[116:117], v[112:113]
	v_exp_f32_e32 v190, v190
	v_exp_f32_e32 v191, v191
	v_exp_f32_e32 v192, v192
	v_exp_f32_e32 v193, v193
	v_pk_mul_f32 v[118:119], v[118:119], v[114:115]
	v_pk_add_f32 v[190:191], v[190:191], v[182:183] op_sel_hi:[1,0]
	v_pk_add_f32 v[192:193], v[192:193], v[182:183] op_sel_hi:[1,0]
	v_pk_mul_f32 v[116:117], v[116:117], v[188:189] op_sel_hi:[1,0]
	v_rcp_f32_e32 v190, v190
	v_rcp_f32_e32 v191, v191
	v_rcp_f32_e32 v192, v192
	v_rcp_f32_e32 v193, v193
	v_pk_mul_f32 v[118:119], v[118:119], v[188:189] op_sel_hi:[1,0]
	v_pk_mul_f32 v[116:117], v[116:117], v[190:191]
	v_pk_mul_f32 v[118:119], v[118:119], v[192:193]
	v_cvt_pk_bf16_f32 v194, v124, v125
	v_cvt_pk_bf16_f32 v195, v126, v127
	v_cvt_pk_bf16_f32 v196, v116, v117
	v_cvt_pk_bf16_f32 v197, v118, v119
	global_store_dwordx4 v[202:203], v[194:197], off
	v_fmamk_f32 v184, v173, 0x3a000000, v164
	v_rsq_f32_e32 v184, v184
	v_lshl_add_u64 v[202:203], v[180:181], 0, v[132:133]
	v_mul_f32_e32 v186, 0xbfb8aa3b, v184
	v_mul_f32_e32 v188, v184, v184
	v_pk_mul_f32 v[190:191], v[108:109], v[186:187] op_sel_hi:[1,0]
	v_pk_mul_f32 v[192:193], v[110:111], v[186:187] op_sel_hi:[1,0]
	v_pk_mul_f32 v[108:109], v[108:109], v[104:105]
	v_exp_f32_e32 v190, v190
	v_exp_f32_e32 v191, v191
	v_exp_f32_e32 v192, v192
	v_exp_f32_e32 v193, v193
	v_pk_mul_f32 v[110:111], v[110:111], v[106:107]
	v_pk_add_f32 v[190:191], v[190:191], v[182:183] op_sel_hi:[1,0]
	v_pk_add_f32 v[192:193], v[192:193], v[182:183] op_sel_hi:[1,0]
	v_pk_mul_f32 v[108:109], v[108:109], v[188:189] op_sel_hi:[1,0]
	v_rcp_f32_e32 v190, v190
	v_rcp_f32_e32 v191, v191
	v_rcp_f32_e32 v192, v192
	v_rcp_f32_e32 v193, v193
	v_pk_mul_f32 v[110:111], v[110:111], v[188:189] op_sel_hi:[1,0]
	v_pk_mul_f32 v[108:109], v[108:109], v[190:191]
	v_pk_mul_f32 v[110:111], v[110:111], v[192:193]
	v_pk_mul_f32 v[190:191], v[100:101], v[186:187] op_sel_hi:[1,0]
	v_pk_mul_f32 v[192:193], v[102:103], v[186:187] op_sel_hi:[1,0]
	v_pk_mul_f32 v[100:101], v[100:101], v[96:97]
	v_exp_f32_e32 v190, v190
	v_exp_f32_e32 v191, v191
	v_exp_f32_e32 v192, v192
	v_exp_f32_e32 v193, v193
	v_pk_mul_f32 v[102:103], v[102:103], v[98:99]
	v_pk_add_f32 v[190:191], v[190:191], v[182:183] op_sel_hi:[1,0]
	v_pk_add_f32 v[192:193], v[192:193], v[182:183] op_sel_hi:[1,0]
	v_pk_mul_f32 v[100:101], v[100:101], v[188:189] op_sel_hi:[1,0]
	v_rcp_f32_e32 v190, v190
	v_rcp_f32_e32 v191, v191
	v_rcp_f32_e32 v192, v192
	v_rcp_f32_e32 v193, v193
	v_pk_mul_f32 v[102:103], v[102:103], v[188:189] op_sel_hi:[1,0]
	v_pk_mul_f32 v[100:101], v[100:101], v[190:191]
	v_pk_mul_f32 v[102:103], v[102:103], v[192:193]
	v_cvt_pk_bf16_f32 v198, v108, v109
	v_cvt_pk_bf16_f32 v199, v110, v111
	v_cvt_pk_bf16_f32 v200, v100, v101
	v_cvt_pk_bf16_f32 v201, v102, v103
	global_store_dwordx4 v[202:203], v[198:201], off
	s_cmp_lg_u64 s[36:37], 0
	s_cbranch_scc0 .Lepi_p1_nb
	s_barrier
; __device__ __forceinline__ float rstd_of(float ss, float inv_n) { return __builtin_amdgcn_rsqf(ss * inv_n + 1e-6f); }
; __device__ __forceinline__ float sigmoid_f(float v) { return __builtin_amdgcn_rcpf(1.0f + __builtin_amdgcn_exp2f(-1.4426950408889634f * v)); }
; __device__ __forceinline__ u32x4 pack8(const f32x4 a, const f32x4 b) { u32x4 w; w.x = cvt_pk_bf16(a[0], a[1]); w.y = cvt_pk_bf16(a[2], a[3]); w.z = cvt_pk_bf16(b[0], b[1]); w.w = cvt_pk_bf16(b[2], b[3]); return w; }
;     __device__ __forceinline__ void operator()(f32x4 (&acc)[2][2][4][2], const Unit& u_, int wr, int wc, int fr, int fq) const {
;     ...
;             for (int m = 0; m < 4; ++m) {
;                 const int row = row0 + ai * HALF + m * 16; const float r = rstd_of(sl[u.par * 256 + ai * HALF + wr * 64 + m * 16 + fr], 1.0f / 2048.0f) * ascale;
;                 f32x4 o[2];
; #pragma unroll
;                 for (int n = 0; n < 2; ++n) { const f32x4 g = acc[ai][0][m][n] * r, uu = acc[ai][1][m][n] * r;
; #pragma unroll
;                     for (int e = 0; e < 4; ++e) o[n][e] = g[e] * uu[e] * sigmoid_f(g[e]); }
;                 if constexpr (F8OUT) {
;                     typedef unsigned u32x2 __attribute__((ext_vector_type(2))); u32x2 w8; w8.x = pack4_fp8(o[0][0] * F8_ACT_SCALE, o[0][1] * F8_ACT_SCALE, o[0][2] * F8_ACT_SCALE, o[0][3] * F8_ACT_SCALE);
;                     w8.y = pack4_fp8(o[1][0] * F8_ACT_SCALE, o[1][1] * F8_ACT_SCALE, o[1][2] * F8_ACT_SCALE, o[1][3] * F8_ACT_SCALE);
;                     *(u32x2*)((unsigned char*)O + (((size_t)u.pm * (ldo / 128) + (col0 >> 7)) * BM + (ai * HALF + wr * 64 + m * 16 + fr)) * 128 + (col0 & 127)) = w8;
;                 } else
;                 *(u32x4*)(O + (((size_t)u.pm * (ldo / 64) + (col0 >> 6)) * BM + (ai * HALF + wr * 64 + m * 16 + fr)) * 64 + (col0 & 63)) = pack8(o[0], o[1]);
.Lepi_p1_nb:
	v_fmamk_f32 v184, v174, 0x3a000000, v164
	v_rsq_f32_e32 v184, v184
	v_lshl_add_u64 v[202:203], v[180:181], 0, v[134:135]
	v_mul_f32_e32 v186, 0xbfb8aa3b, v184
	v_mul_f32_e32 v188, v184, v184
	v_pk_mul_f32 v[190:191], v[92:93], v[186:187] op_sel_hi:[1,0]
	v_pk_mul_f32 v[192:193], v[94:95], v[186:187] op_sel_hi:[1,0]
	v_pk_mul_f32 v[92:93], v[92:93], v[88:89]
	v_exp_f32_e32 v190, v190
	v_exp_f32_e32 v191, v191
	v_exp_f32_e32 v192, v192
	v_exp_f32_e32 v193, v193
	v_pk_mul_f32 v[94:95], v[94:95], v[90:91]
	v_pk_add_f32 v[190:191], v[190:191], v[182:183] op_sel_hi:[1,0]
	v_pk_add_f32 v[192:193], v[192:193], v[182:183] op_sel_hi:[1,0]
	v_pk_mul_f32 v[92:93], v[92:93], v[188:189] op_sel_hi:[1,0]
	v_rcp_f32_e32 v190, v190
	v_rcp_f32_e32 v191, v191
	v_rcp_f32_e32 v192, v192
	v_rcp_f32_e32 v193, v193
	v_pk_mul_f32 v[94:95], v[94:95], v[188:189] op_sel_hi:[1,0]
	v_pk_mul_f32 v[92:93], v[92:93], v[190:191]
	v_pk_mul_f32 v[94:95], v[94:95], v[192:193]
	v_pk_mul_f32 v[190:191], v[84:85], v[186:187] op_sel_hi:[1,0]
	v_pk_mul_f32 v[192:193], v[86:87], v[186:187] op_sel_hi:[1,0]
	v_pk_mul_f32 v[84:85], v[84:85], v[80:81]
	v_exp_f32_e32 v190, v190
	v_exp_f32_e32 v191, v191
	v_exp_f32_e32 v192, v192
	v_exp_f32_e32 v193, v193
	v_pk_mul_f32 v[86:87], v[86:87], v[82:83]
	v_pk_add_f32 v[190:191], v[190:191], v[182:183] op_sel_hi:[1,0]
	v_pk_add_f32 v[192:193], v[192:193], v[182:183] op_sel_hi:[1,0]
	v_pk_mul_f32 v[84:85], v[84:85], v[188:189] op_sel_hi:[1,0]
	v_rcp_f32_e32 v190, v190
	v_rcp_f32_e32 v191, v191
	v_rcp_f32_e32 v192, v192
	v_rcp_f32_e32 v193, v193
	v_pk_mul_f32 v[86:87], v[86:87], v[188:189] op_sel_hi:[1,0]
	v_pk_mul_f32 v[84:85], v[84:85], v[190:191]
	v_pk_mul_f32 v[86:87], v[86:87], v[192:193]
	v_cvt_pk_bf16_f32 v194, v92, v93
	v_cvt_pk_bf16_f32 v195, v94, v95
	v_cvt_pk_bf16_f32 v196, v84, v85
	v_cvt_pk_bf16_f32 v197, v86, v87
	global_store_dwordx4 v[202:203], v[194:197], off
	v_fmamk_f32 v184, v175, 0x3a000000, v164
	v_rsq_f32_e32 v184, v184
	v_lshl_add_u64 v[202:203], v[180:181], 0, v[136:137]
	v_mul_f32_e32 v186, 0xbfb8aa3b, v184
	v_mul_f32_e32 v188, v184, v184
	v_pk_mul_f32 v[190:191], v[76:77], v[186:187] op_sel_hi:[1,0]
	v_pk_mul_f32 v[192:193], v[78:79], v[186:187] op_sel_hi:[1,0]
	v_pk_mul_f32 v[76:77], v[76:77], v[72:73]
	v_exp_f32_e32 v190, v190
	v_exp_f32_e32 v191, v191
	v_exp_f32_e32 v192, v192
	v_exp_f32_e32 v193, v193
	v_pk_mul_f32 v[78:79], v[78:79], v[74:75]
	v_pk_add_f32 v[190:191], v[190:191], v[182:183] op_sel_hi:[1,0]
	v_pk_add_f32 v[192:193], v[192:193], v[182:183] op_sel_hi:[1,0]
	v_pk_mul_f32 v[76:77], v[76:77], v[188:189] op_sel_hi:[1,0]
	v_rcp_f32_e32 v190, v190
	v_rcp_f32_e32 v191, v191
	v_rcp_f32_e32 v192, v192
	v_rcp_f32_e32 v193, v193
	v_pk_mul_f32 v[78:79], v[78:79], v[188:189] op_sel_hi:[1,0]
	v_pk_mul_f32 v[76:77], v[76:77], v[190:191]
	v_pk_mul_f32 v[78:79], v[78:79], v[192:193]
	v_pk_mul_f32 v[190:191], v[68:69], v[186:187] op_sel_hi:[1,0]
	v_pk_mul_f32 v[192:193], v[70:71], v[186:187] op_sel_hi:[1,0]
	v_pk_mul_f32 v[68:69], v[68:69], v[64:65]
	v_exp_f32_e32 v190, v190
	v_exp_f32_e32 v191, v191
	v_exp_f32_e32 v192, v192
	v_exp_f32_e32 v193, v193
	v_pk_mul_f32 v[70:71], v[70:71], v[66:67]
	v_pk_add_f32 v[190:191], v[190:191], v[182:183] op_sel_hi:[1,0]
	v_pk_add_f32 v[192:193], v[192:193], v[182:183] op_sel_hi:[1,0]
	v_pk_mul_f32 v[68:69], v[68:69], v[188:189] op_sel_hi:[1,0]
	v_rcp_f32_e32 v190, v190
	v_rcp_f32_e32 v191, v191
	v_rcp_f32_e32 v192, v192
	v_rcp_f32_e32 v193, v193
	v_pk_mul_f32 v[70:71], v[70:71], v[188:189] op_sel_hi:[1,0]
	v_pk_mul_f32 v[68:69], v[68:69], v[190:191]
	v_pk_mul_f32 v[70:71], v[70:71], v[192:193]
	v_cvt_pk_bf16_f32 v198, v76, v77
	v_cvt_pk_bf16_f32 v199, v78, v79
	v_cvt_pk_bf16_f32 v200, v68, v69
	v_cvt_pk_bf16_f32 v201, v70, v71
	global_store_dwordx4 v[202:203], v[198:201], off
	v_fmamk_f32 v184, v176, 0x3a000000, v164
	v_rsq_f32_e32 v184, v184
	v_lshl_add_u64 v[202:203], v[180:181], 0, v[138:139]
	v_mul_f32_e32 v186, 0xbfb8aa3b, v184
	v_mul_f32_e32 v188, v184, v184
	v_pk_mul_f32 v[190:191], v[60:61], v[186:187] op_sel_hi:[1,0]
	v_pk_mul_f32 v[192:193], v[62:63], v[186:187] op_sel_hi:[1,0]
	v_pk_mul_f32 v[60:61], v[60:61], v[56:57]
	v_exp_f32_e32 v190, v190
	v_exp_f32_e32 v191, v191
	v_exp_f32_e32 v192, v192
	v_exp_f32_e32 v193, v193
	v_pk_mul_f32 v[62:63], v[62:63], v[58:59]
	v_pk_add_f32 v[190:191], v[190:191], v[182:183] op_sel_hi:[1,0]
	v_pk_add_f32 v[192:193], v[192:193], v[182:183] op_sel_hi:[1,0]
	v_pk_mul_f32 v[60:61], v[60:61], v[188:189] op_sel_hi:[1,0]
	v_rcp_f32_e32 v190, v190
	v_rcp_f32_e32 v191, v191
	v_rcp_f32_e32 v192, v192
	v_rcp_f32_e32 v193, v193
	v_pk_mul_f32 v[62:63], v[62:63], v[188:189] op_sel_hi:[1,0]
	v_pk_mul_f32 v[60:61], v[60:61], v[190:191]
	v_pk_mul_f32 v[62:63], v[62:63], v[192:193]
	v_pk_mul_f32 v[190:191], v[52:53], v[186:187] op_sel_hi:[1,0]
	v_pk_mul_f32 v[192:193], v[54:55], v[186:187] op_sel_hi:[1,0]
	v_pk_mul_f32 v[52:53], v[52:53], v[48:49]
	v_exp_f32_e32 v190, v190
	v_exp_f32_e32 v191, v191
	v_exp_f32_e32 v192, v192
	v_exp_f32_e32 v193, v193
	v_pk_mul_f32 v[54:55], v[54:55], v[50:51]
	v_pk_add_f32 v[190:191], v[190:191], v[182:183] op_sel_hi:[1,0]
	v_pk_add_f32 v[192:193], v[192:193], v[182:183] op_sel_hi:[1,0]
	v_pk_mul_f32 v[52:53], v[52:53], v[188:189] op_sel_hi:[1,0]
	v_rcp_f32_e32 v190, v190
	v_rcp_f32_e32 v191, v191
	v_rcp_f32_e32 v192, v192
	v_rcp_f32_e32 v193, v193
	v_pk_mul_f32 v[54:55], v[54:55], v[188:189] op_sel_hi:[1,0]
	v_pk_mul_f32 v[52:53], v[52:53], v[190:191]
	v_pk_mul_f32 v[54:55], v[54:55], v[192:193]
	v_cvt_pk_bf16_f32 v194, v60, v61
	v_cvt_pk_bf16_f32 v195, v62, v63
	v_cvt_pk_bf16_f32 v196, v52, v53
; __device__ __forceinline__ float rstd_of(float ss, float inv_n) { return __builtin_amdgcn_rsqf(ss * inv_n + 1e-6f); }
; #define PG8_BAR __builtin_amdgcn_s_barrier()
;     __device__ __forceinline__ void operator()(f32x4 (&acc)[2][2][4][2], const Unit& u_, int wr, int wc, int fr, int fq) const {
;     ...
;             for (int m = 0; m < 4; ++m) {
;                 const int row = row0 + ai * HALF + m * 16; const float r = rstd_of(sl[u.par * 256 + ai * HALF + wr * 64 + m * 16 + fr], 1.0f / 2048.0f) * ascale;
;                 f32x4 o[2];
; #pragma unroll
;                 for (int n = 0; n < 2; ++n) { const f32x4 g = acc[ai][0][m][n] * r, uu = acc[ai][1][m][n] * r;
; #pragma unroll
;                     for (int e = 0; e < 4; ++e) o[n][e] = g[e] * uu[e] * sigmoid_f(g[e]); }
;                 if constexpr (F8OUT) {
;                     typedef unsigned u32x2 __attribute__((ext_vector_type(2))); u32x2 w8; w8.x = pack4_fp8(o[0][0] * F8_ACT_SCALE, o[0][1] * F8_ACT_SCALE, o[0][2] * F8_ACT_SCALE, o[0][3] * F8_ACT_SCALE);
;                     w8.y = pack4_fp8(o[1][0] * F8_ACT_SCALE, o[1][1] * F8_ACT_SCALE, o[1][2] * F8_ACT_SCALE, o[1][3] * F8_ACT_SCALE);
;                     *(u32x2*)((unsigned char*)O + (((size_t)u.pm * (ldo / 128) + (col0 >> 7)) * BM + (ai * HALF + wr * 64 + m * 16 + fr)) * 128 + (col0 & 127)) = w8;
;                 } else
;                 *(u32x4*)(O + (((size_t)u.pm * (ldo / 64) + (col0 >> 6)) * BM + (ai * HALF + wr * 64 + m * 16 + fr)) * 64 + (col0 & 63)) = pack8(o[0], o[1]);
; template <class Epi, class Sched, bool ALIGN_EPI = false, bool SP2 = false, bool ABLK = false, bool F8 = false>
; __device__ __forceinline__ void gemm_phase(PG8_LAS unsigned char* lds, const Gemm g, const Sched& S, const Epi& E, const int wave_s) {
;     ...
;         if constexpr (!Epi::AFTER_DRAIN) { E(acc, cur, wr, wc, fr, fq); S.done(cur); }
;         if (!has_next) break;
;         if (!(Epi::MID && cur.kh == 0))
; #pragma unroll
;         for (int a = 0; a < 2; ++a)
; #pragma unroll
;             for (int b = 0; b < 2; ++b)
; #pragma unroll
;                 for (int m = 0; m < 4; ++m)
; #pragma unroll
;                     for (int n = 0; n < 2; ++n) acc[a][b][m][n] = (f32x4){0.f, 0.f, 0.f, 0.f};
;         cur = nxt; cA = nA; cB = nB; ++ui;
;         if constexpr (ALIGN_EPI) { if (wr == 1) PG8_BAR; }
	v_cvt_pk_bf16_f32 v197, v54, v55
	global_store_dwordx4 v[202:203], v[194:197], off
	v_fmamk_f32 v184, v177, 0x3a000000, v164
	v_rsq_f32_e32 v184, v184
	v_lshl_add_u64 v[202:203], v[180:181], 0, v[140:141]
	v_mul_f32_e32 v186, 0xbfb8aa3b, v184
	v_mul_f32_e32 v188, v184, v184
	v_pk_mul_f32 v[190:191], v[44:45], v[186:187] op_sel_hi:[1,0]
	v_pk_mul_f32 v[192:193], v[46:47], v[186:187] op_sel_hi:[1,0]
	v_pk_mul_f32 v[44:45], v[44:45], v[40:41]
	v_exp_f32_e32 v190, v190
	v_exp_f32_e32 v191, v191
	v_exp_f32_e32 v192, v192
	v_exp_f32_e32 v193, v193
	v_pk_mul_f32 v[46:47], v[46:47], v[42:43]
	v_pk_add_f32 v[190:191], v[190:191], v[182:183] op_sel_hi:[1,0]
	v_pk_add_f32 v[192:193], v[192:193], v[182:183] op_sel_hi:[1,0]
	v_pk_mul_f32 v[44:45], v[44:45], v[188:189] op_sel_hi:[1,0]
	v_rcp_f32_e32 v190, v190
	v_rcp_f32_e32 v191, v191
	v_rcp_f32_e32 v192, v192
	v_rcp_f32_e32 v193, v193
	v_pk_mul_f32 v[46:47], v[46:47], v[188:189] op_sel_hi:[1,0]
	v_pk_mul_f32 v[44:45], v[44:45], v[190:191]
	v_pk_mul_f32 v[46:47], v[46:47], v[192:193]
	v_pk_mul_f32 v[190:191], v[36:37], v[186:187] op_sel_hi:[1,0]
	v_pk_mul_f32 v[192:193], v[38:39], v[186:187] op_sel_hi:[1,0]
	v_pk_mul_f32 v[36:37], v[36:37], v[32:33]
	v_exp_f32_e32 v190, v190
	v_exp_f32_e32 v191, v191
	v_exp_f32_e32 v192, v192
	v_exp_f32_e32 v193, v193
	v_pk_mul_f32 v[38:39], v[38:39], v[34:35]
	v_pk_add_f32 v[190:191], v[190:191], v[182:183] op_sel_hi:[1,0]
	v_pk_add_f32 v[192:193], v[192:193], v[182:183] op_sel_hi:[1,0]
	v_pk_mul_f32 v[36:37], v[36:37], v[188:189] op_sel_hi:[1,0]
	v_rcp_f32_e32 v190, v190
	v_rcp_f32_e32 v191, v191
	v_rcp_f32_e32 v192, v192
	v_rcp_f32_e32 v193, v193
	v_pk_mul_f32 v[38:39], v[38:39], v[188:189] op_sel_hi:[1,0]
	v_pk_mul_f32 v[36:37], v[36:37], v[190:191]
	v_pk_mul_f32 v[38:39], v[38:39], v[192:193]
	v_cvt_pk_bf16_f32 v198, v44, v45
	v_cvt_pk_bf16_f32 v199, v46, v47
	v_cvt_pk_bf16_f32 v200, v36, v37
	v_cvt_pk_bf16_f32 v201, v38, v39
	global_store_dwordx4 v[202:203], v[198:201], off
	v_fmamk_f32 v184, v178, 0x3a000000, v164
	v_rsq_f32_e32 v184, v184
	v_lshl_add_u64 v[202:203], v[180:181], 0, v[142:143]
	v_mul_f32_e32 v186, 0xbfb8aa3b, v184
	v_mul_f32_e32 v188, v184, v184
	v_pk_mul_f32 v[190:191], v[28:29], v[186:187] op_sel_hi:[1,0]
	v_pk_mul_f32 v[192:193], v[30:31], v[186:187] op_sel_hi:[1,0]
	v_pk_mul_f32 v[28:29], v[28:29], v[24:25]
	v_exp_f32_e32 v190, v190
	v_exp_f32_e32 v191, v191
	v_exp_f32_e32 v192, v192
	v_exp_f32_e32 v193, v193
	v_pk_mul_f32 v[30:31], v[30:31], v[26:27]
	v_pk_add_f32 v[190:191], v[190:191], v[182:183] op_sel_hi:[1,0]
	v_pk_add_f32 v[192:193], v[192:193], v[182:183] op_sel_hi:[1,0]
	v_pk_mul_f32 v[28:29], v[28:29], v[188:189] op_sel_hi:[1,0]
	v_rcp_f32_e32 v190, v190
	v_rcp_f32_e32 v191, v191
	v_rcp_f32_e32 v192, v192
	v_rcp_f32_e32 v193, v193
	v_pk_mul_f32 v[30:31], v[30:31], v[188:189] op_sel_hi:[1,0]
	v_pk_mul_f32 v[28:29], v[28:29], v[190:191]
	v_pk_mul_f32 v[30:31], v[30:31], v[192:193]
	v_pk_mul_f32 v[190:191], v[20:21], v[186:187] op_sel_hi:[1,0]
	v_pk_mul_f32 v[192:193], v[22:23], v[186:187] op_sel_hi:[1,0]
	v_pk_mul_f32 v[20:21], v[20:21], v[16:17]
	v_exp_f32_e32 v190, v190
	v_exp_f32_e32 v191, v191
	v_exp_f32_e32 v192, v192
	v_exp_f32_e32 v193, v193
	v_pk_mul_f32 v[22:23], v[22:23], v[18:19]
	v_pk_add_f32 v[190:191], v[190:191], v[182:183] op_sel_hi:[1,0]
	v_pk_add_f32 v[192:193], v[192:193], v[182:183] op_sel_hi:[1,0]
	v_pk_mul_f32 v[20:21], v[20:21], v[188:189] op_sel_hi:[1,0]
	v_rcp_f32_e32 v190, v190
	v_rcp_f32_e32 v191, v191
	v_rcp_f32_e32 v192, v192
	v_rcp_f32_e32 v193, v193
	v_pk_mul_f32 v[22:23], v[22:23], v[188:189] op_sel_hi:[1,0]
	v_pk_mul_f32 v[20:21], v[20:21], v[190:191]
	v_pk_mul_f32 v[22:23], v[22:23], v[192:193]
	v_cvt_pk_bf16_f32 v194, v28, v29
	v_cvt_pk_bf16_f32 v195, v30, v31
	v_cvt_pk_bf16_f32 v196, v20, v21
	v_cvt_pk_bf16_f32 v197, v22, v23
	global_store_dwordx4 v[202:203], v[194:197], off
	v_fmamk_f32 v184, v179, 0x3a000000, v164
	v_rsq_f32_e32 v184, v184
	v_lshl_add_u64 v[202:203], v[180:181], 0, v[144:145]
	v_mul_f32_e32 v186, 0xbfb8aa3b, v184
	v_mul_f32_e32 v188, v184, v184
	v_pk_mul_f32 v[190:191], v[12:13], v[186:187] op_sel_hi:[1,0]
	v_pk_mul_f32 v[192:193], v[14:15], v[186:187] op_sel_hi:[1,0]
	v_pk_mul_f32 v[12:13], v[12:13], v[8:9]
	v_exp_f32_e32 v190, v190
	v_exp_f32_e32 v191, v191
	v_exp_f32_e32 v192, v192
	v_exp_f32_e32 v193, v193
	v_pk_mul_f32 v[14:15], v[14:15], v[10:11]
	v_pk_add_f32 v[190:191], v[190:191], v[182:183] op_sel_hi:[1,0]
	v_pk_add_f32 v[192:193], v[192:193], v[182:183] op_sel_hi:[1,0]
	v_pk_mul_f32 v[12:13], v[12:13], v[188:189] op_sel_hi:[1,0]
	v_rcp_f32_e32 v190, v190
	v_rcp_f32_e32 v191, v191
	v_rcp_f32_e32 v192, v192
	v_rcp_f32_e32 v193, v193
	v_pk_mul_f32 v[14:15], v[14:15], v[188:189] op_sel_hi:[1,0]
	v_pk_mul_f32 v[12:13], v[12:13], v[190:191]
	v_pk_mul_f32 v[14:15], v[14:15], v[192:193]
	v_pk_mul_f32 v[190:191], v[4:5], v[186:187] op_sel_hi:[1,0]
	v_pk_mul_f32 v[192:193], v[6:7], v[186:187] op_sel_hi:[1,0]
	v_pk_mul_f32 v[4:5], v[4:5], v[0:1]
	v_exp_f32_e32 v190, v190
	v_exp_f32_e32 v191, v191
	v_exp_f32_e32 v192, v192
	v_exp_f32_e32 v193, v193
	v_pk_mul_f32 v[6:7], v[6:7], v[2:3]
	v_pk_add_f32 v[190:191], v[190:191], v[182:183] op_sel_hi:[1,0]
	v_pk_add_f32 v[192:193], v[192:193], v[182:183] op_sel_hi:[1,0]
	v_pk_mul_f32 v[4:5], v[4:5], v[188:189] op_sel_hi:[1,0]
	v_rcp_f32_e32 v190, v190
	v_rcp_f32_e32 v191, v191
	v_rcp_f32_e32 v192, v192
	v_rcp_f32_e32 v193, v193
	v_pk_mul_f32 v[6:7], v[6:7], v[188:189] op_sel_hi:[1,0]
	v_pk_mul_f32 v[4:5], v[4:5], v[190:191]
	v_pk_mul_f32 v[6:7], v[6:7], v[192:193]
	v_cvt_pk_bf16_f32 v198, v12, v13
	v_cvt_pk_bf16_f32 v199, v14, v15
	v_cvt_pk_bf16_f32 v200, v4, v5
	v_cvt_pk_bf16_f32 v201, v6, v7
	global_store_dwordx4 v[202:203], v[198:201], off
	s_cbranch_vccnz .LBB0_219
	s_and_b64 vcc, exec, s[10:11]
	s_cbranch_vccnz .LBB0_218
	s_barrier
	s_branch .LBB0_218

; __device__ __forceinline__ float rstd_of(float ss, float inv_n) { return __builtin_amdgcn_rsqf(ss * inv_n + 1e-6f); }
; __device__ __forceinline__ float sigmoid_f(float v) { return __builtin_amdgcn_rcpf(1.0f + __builtin_amdgcn_exp2f(-1.4426950408889634f * v)); }
; #define PG8_BAR __builtin_amdgcn_s_barrier()
;     __device__ __forceinline__ void operator()(f32x4 (&acc)[2][2][4][2], const Unit& u_, int wr, int wc, int fr, int fq) const {
;         Unit u = u_; if constexpr (OPQ) { unsigned o1_ = ~0u; asm volatile("" : "+s"(u.pm), "+s"(u.pn), "+s"(o1_)); const int l_ = (int)__builtin_amdgcn_mbcnt_hi(o1_, __builtin_amdgcn_mbcnt_lo(o1_, 0u)); fr = l_ & 15; fq = l_ >> 4; }
;         const int row0 = u.pm * BM + wr * 64 + fr, col0 = u.pn * HALF + wc * 32 + 8 * fq;
; #pragma unroll
;         for (int ai = 0; ai < 2; ++ai)
; #pragma unroll
;             for (int m = 0; m < 4; ++m) {
;                 const int row = row0 + ai * HALF + m * 16; const float r = rstd_of(sl[u.par * 256 + ai * HALF + wr * 64 + m * 16 + fr], 1.0f / 2048.0f) * ascale;
;                 f32x4 o[2];
; #pragma unroll
;                 for (int n = 0; n < 2; ++n) { const f32x4 g = acc[ai][0][m][n] * r, uu = acc[ai][1][m][n] * r;
; #pragma unroll
;                     for (int e = 0; e < 4; ++e) o[n][e] = g[e] * uu[e] * sigmoid_f(g[e]); }
;                 if constexpr (F8OUT) {
;                     typedef unsigned u32x2 __attribute__((ext_vector_type(2))); u32x2 w8; w8.x = pack4_fp8(o[0][0] * F8_ACT_SCALE, o[0][1] * F8_ACT_SCALE, o[0][2] * F8_ACT_SCALE, o[0][3] * F8_ACT_SCALE);
;                     w8.y = pack4_fp8(o[1][0] * F8_ACT_SCALE, o[1][1] * F8_ACT_SCALE, o[1][2] * F8_ACT_SCALE, o[1][3] * F8_ACT_SCALE);
;                     *(u32x2*)((unsigned char*)O + (((size_t)u.pm * (ldo / 128) + (col0 >> 7)) * BM + (ai * HALF + wr * 64 + m * 16 + fr)) * 128 + (col0 & 127)) = w8;
;                 } else
;                 *(u32x4*)(O + (((size_t)u.pm * (ldo / 64) + (col0 >> 6)) * BM + (ai * HALF + wr * 64 + m * 16 + fr)) * 64 + (col0 & 63)) = pack8(o[0], o[1]);
; template <class Epi, class Sched, bool ALIGN_EPI = false, bool SP2 = false, bool ABLK = false, bool F8 = false>
; __device__ __forceinline__ void gemm_phase(PG8_LAS unsigned char* lds, const Gemm g, const Sched& S, const Epi& E, const int wave_s) {
;     ...
;         if constexpr (ALIGN_EPI) { if (wr == 0) PG8_BAR; }
.LBB0_815:
	s_lshl_b32 s11, s65, 10
	v_mbcnt_lo_u32_b32 v168, -1, 0
	v_mbcnt_hi_u32_b32 v168, -1, v168
	s_add_i32 s11, s53, s11
	v_and_b32_e32 v169, 15, v168
	v_lshl_add_u32 v166, v169, 2, s11
	ds_read_b32 v172, v166
	ds_read_b32 v173, v166 offset:64
	ds_read_b32 v174, v166 offset:128
	ds_read_b32 v175, v166 offset:192
	ds_read_b32 v176, v166 offset:512
	ds_read_b32 v177, v166 offset:576
	ds_read_b32 v178, v166 offset:640
	ds_read_b32 v179, v166 offset:704
	s_lshl_b32 s10, s52, 7
	v_lshrrev_b32_e32 v168, 1, v168
	s_or_b32 s10, s10, s91
	v_and_b32_e32 v168, 56, v168
	v_add_u32_e32 v167, s10, v168
	s_andn2_b64 vcc, exec, s[8:9]
	s_mov_b64 s[8:9], -1
	v_or_b32_e32 v170, s94, v169
	v_mov_b32_e32 v171, 0
	v_ashrrev_i32_e32 v168, 6, v167
	v_ashrrev_i32_e32 v169, 31, v168
	v_mad_i64_i32 v[180:181], s[10:11], s50, v146, v[168:169]
	v_lshlrev_b64 v[170:171], 7, v[170:171]
	v_lshlrev_b64 v[180:181], 15, v[180:181]
	v_and_b32_e32 v168, 56, v167
	v_lshl_add_u64 v[180:181], s[34:35], 0, v[180:181]
	v_lshlrev_b32_e32 v168, 1, v168
	v_mov_b32_e32 v169, 0
	v_lshl_add_u64 v[180:181], v[180:181], 0, v[170:171]
	v_mov_b32_e32 v182, 1.0
	v_lshl_add_u64 v[180:181], v[180:181], 0, v[168:169]
	s_mov_b64 s[10:11], 0x1000
	v_lshl_add_u64 v[202:203], v[180:181], 0, s[10:11]
	s_mov_b64 s[10:11], 0x5000
	v_lshl_add_u64 v[204:205], v[180:181], 0, s[10:11]
	s_waitcnt lgkmcnt(0)
	v_fmamk_f32 v184, v172, 0x3a000000, v145
	v_rsq_f32_e32 v184, v184
	s_nop 0
	v_mul_f32_e32 v184, 0x3a800000, v184
	v_mul_f32_e32 v186, 0xbfb8aa3b, v184
	v_mul_f32_e32 v188, v184, v184
	v_pk_mul_f32 v[190:191], v[124:125], v[186:187] op_sel_hi:[1,0]
	v_pk_mul_f32 v[192:193], v[126:127], v[186:187] op_sel_hi:[1,0]
	v_pk_mul_f32 v[124:125], v[124:125], v[120:121]
	v_exp_f32_e32 v190, v190
	v_exp_f32_e32 v191, v191
	v_exp_f32_e32 v192, v192
	v_exp_f32_e32 v193, v193
	v_pk_mul_f32 v[126:127], v[126:127], v[122:123]
	v_pk_add_f32 v[190:191], v[190:191], v[182:183] op_sel_hi:[1,0]
	v_pk_add_f32 v[192:193], v[192:193], v[182:183] op_sel_hi:[1,0]
	v_pk_mul_f32 v[124:125], v[124:125], v[188:189] op_sel_hi:[1,0]
	v_rcp_f32_e32 v190, v190
	v_rcp_f32_e32 v191, v191
	v_rcp_f32_e32 v192, v192
	v_rcp_f32_e32 v193, v193
	v_pk_mul_f32 v[126:127], v[126:127], v[188:189] op_sel_hi:[1,0]
	v_pk_mul_f32 v[124:125], v[124:125], v[190:191]
	v_pk_mul_f32 v[126:127], v[126:127], v[192:193]
	v_pk_mul_f32 v[190:191], v[116:117], v[186:187] op_sel_hi:[1,0]
	v_pk_mul_f32 v[192:193], v[118:119], v[186:187] op_sel_hi:[1,0]
	v_pk_mul_f32 v[116:117], v[116:117], v[112:113]
	v_exp_f32_e32 v190, v190
	v_exp_f32_e32 v191, v191
	v_exp_f32_e32 v192, v192
	v_exp_f32_e32 v193, v193
	v_pk_mul_f32 v[118:119], v[118:119], v[114:115]
	v_pk_add_f32 v[190:191], v[190:191], v[182:183] op_sel_hi:[1,0]
	v_pk_add_f32 v[192:193], v[192:193], v[182:183] op_sel_hi:[1,0]
	v_pk_mul_f32 v[116:117], v[116:117], v[188:189] op_sel_hi:[1,0]
	v_rcp_f32_e32 v190, v190
	v_rcp_f32_e32 v191, v191
	v_rcp_f32_e32 v192, v192
	v_rcp_f32_e32 v193, v193
	v_pk_mul_f32 v[118:119], v[118:119], v[188:189] op_sel_hi:[1,0]
	v_pk_mul_f32 v[116:117], v[116:117], v[190:191]
	v_pk_mul_f32 v[118:119], v[118:119], v[192:193]
	v_cvt_pk_bf16_f32 v194, v124, v125
	v_cvt_pk_bf16_f32 v195, v126, v127
	v_cvt_pk_bf16_f32 v196, v116, v117
	v_cvt_pk_bf16_f32 v197, v118, v119
	global_store_dwordx4 v[202:203], v[194:197], off offset:-4096
	v_fmamk_f32 v184, v173, 0x3a000000, v145
	v_rsq_f32_e32 v184, v184
	s_nop 0
	v_mul_f32_e32 v184, 0x3a800000, v184
	v_mul_f32_e32 v186, 0xbfb8aa3b, v184
	v_mul_f32_e32 v188, v184, v184
	v_pk_mul_f32 v[190:191], v[108:109], v[186:187] op_sel_hi:[1,0]
	v_pk_mul_f32 v[192:193], v[110:111], v[186:187] op_sel_hi:[1,0]
	v_pk_mul_f32 v[108:109], v[108:109], v[104:105]
	v_exp_f32_e32 v190, v190
	v_exp_f32_e32 v191, v191
	v_exp_f32_e32 v192, v192
	v_exp_f32_e32 v193, v193
	v_pk_mul_f32 v[110:111], v[110:111], v[106:107]
	v_pk_add_f32 v[190:191], v[190:191], v[182:183] op_sel_hi:[1,0]
	v_pk_add_f32 v[192:193], v[192:193], v[182:183] op_sel_hi:[1,0]
	v_pk_mul_f32 v[108:109], v[108:109], v[188:189] op_sel_hi:[1,0]
	v_rcp_f32_e32 v190, v190
	v_rcp_f32_e32 v191, v191
	v_rcp_f32_e32 v192, v192
	v_rcp_f32_e32 v193, v193
	v_pk_mul_f32 v[110:111], v[110:111], v[188:189] op_sel_hi:[1,0]
	v_pk_mul_f32 v[108:109], v[108:109], v[190:191]
	v_pk_mul_f32 v[110:111], v[110:111], v[192:193]
	v_pk_mul_f32 v[190:191], v[100:101], v[186:187] op_sel_hi:[1,0]
	v_pk_mul_f32 v[192:193], v[102:103], v[186:187] op_sel_hi:[1,0]
	v_pk_mul_f32 v[100:101], v[100:101], v[96:97]
	v_exp_f32_e32 v190, v190
	v_exp_f32_e32 v191, v191
	v_exp_f32_e32 v192, v192
	v_exp_f32_e32 v193, v193
	v_pk_mul_f32 v[102:103], v[102:103], v[98:99]
	v_pk_add_f32 v[190:191], v[190:191], v[182:183] op_sel_hi:[1,0]
	v_pk_add_f32 v[192:193], v[192:193], v[182:183] op_sel_hi:[1,0]
	v_pk_mul_f32 v[100:101], v[100:101], v[188:189] op_sel_hi:[1,0]
	v_rcp_f32_e32 v190, v190
	v_rcp_f32_e32 v191, v191
	v_rcp_f32_e32 v192, v192
	v_rcp_f32_e32 v193, v193
	v_pk_mul_f32 v[102:103], v[102:103], v[188:189] op_sel_hi:[1,0]
	v_pk_mul_f32 v[100:101], v[100:101], v[190:191]
	v_pk_mul_f32 v[102:103], v[102:103], v[192:193]
	v_cvt_pk_bf16_f32 v198, v108, v109
	v_cvt_pk_bf16_f32 v199, v110, v111
	v_cvt_pk_bf16_f32 v200, v100, v101
	v_cvt_pk_bf16_f32 v201, v102, v103
	global_store_dwordx4 v[202:203], v[198:201], off offset:-2048
	s_cmp_lg_u64 s[36:37], 0
	s_cbranch_scc0 .Lepi_p7_nb
	s_barrier
; __device__ __forceinline__ float rstd_of(float ss, float inv_n) { return __builtin_amdgcn_rsqf(ss * inv_n + 1e-6f); }
; __device__ __forceinline__ float sigmoid_f(float v) { return __builtin_amdgcn_rcpf(1.0f + __builtin_amdgcn_exp2f(-1.4426950408889634f * v)); }
; __device__ __forceinline__ u32x4 pack8(const f32x4 a, const f32x4 b) { u32x4 w; w.x = cvt_pk_bf16(a[0], a[1]); w.y = cvt_pk_bf16(a[2], a[3]); w.z = cvt_pk_bf16(b[0], b[1]); w.w = cvt_pk_bf16(b[2], b[3]); return w; }
;     __device__ __forceinline__ void operator()(f32x4 (&acc)[2][2][4][2], const Unit& u_, int wr, int wc, int fr, int fq) const {
;     ...
;             for (int m = 0; m < 4; ++m) {
;                 const int row = row0 + ai * HALF + m * 16; const float r = rstd_of(sl[u.par * 256 + ai * HALF + wr * 64 + m * 16 + fr], 1.0f / 2048.0f) * ascale;
;                 f32x4 o[2];
; #pragma unroll
;                 for (int n = 0; n < 2; ++n) { const f32x4 g = acc[ai][0][m][n] * r, uu = acc[ai][1][m][n] * r;
; #pragma unroll
;                     for (int e = 0; e < 4; ++e) o[n][e] = g[e] * uu[e] * sigmoid_f(g[e]); }
;                 if constexpr (F8OUT) {
;                     typedef unsigned u32x2 __attribute__((ext_vector_type(2))); u32x2 w8; w8.x = pack4_fp8(o[0][0] * F8_ACT_SCALE, o[0][1] * F8_ACT_SCALE, o[0][2] * F8_ACT_SCALE, o[0][3] * F8_ACT_SCALE);
;                     w8.y = pack4_fp8(o[1][0] * F8_ACT_SCALE, o[1][1] * F8_ACT_SCALE, o[1][2] * F8_ACT_SCALE, o[1][3] * F8_ACT_SCALE);
;                     *(u32x2*)((unsigned char*)O + (((size_t)u.pm * (ldo / 128) + (col0 >> 7)) * BM + (ai * HALF + wr * 64 + m * 16 + fr)) * 128 + (col0 & 127)) = w8;
;                 } else
;                 *(u32x4*)(O + (((size_t)u.pm * (ldo / 64) + (col0 >> 6)) * BM + (ai * HALF + wr * 64 + m * 16 + fr)) * 64 + (col0 & 63)) = pack8(o[0], o[1]);
.Lepi_p7_nb:
	v_fmamk_f32 v184, v174, 0x3a000000, v145
	v_rsq_f32_e32 v184, v184
	s_nop 0
	v_mul_f32_e32 v184, 0x3a800000, v184
	v_mul_f32_e32 v186, 0xbfb8aa3b, v184
	v_mul_f32_e32 v188, v184, v184
	v_pk_mul_f32 v[190:191], v[92:93], v[186:187] op_sel_hi:[1,0]
	v_pk_mul_f32 v[192:193], v[94:95], v[186:187] op_sel_hi:[1,0]
	v_pk_mul_f32 v[92:93], v[92:93], v[88:89]
	v_exp_f32_e32 v190, v190
	v_exp_f32_e32 v191, v191
	v_exp_f32_e32 v192, v192
	v_exp_f32_e32 v193, v193
	v_pk_mul_f32 v[94:95], v[94:95], v[90:91]
	v_pk_add_f32 v[190:191], v[190:191], v[182:183] op_sel_hi:[1,0]
	v_pk_add_f32 v[192:193], v[192:193], v[182:183] op_sel_hi:[1,0]
	v_pk_mul_f32 v[92:93], v[92:93], v[188:189] op_sel_hi:[1,0]
	v_rcp_f32_e32 v190, v190
	v_rcp_f32_e32 v191, v191
	v_rcp_f32_e32 v192, v192
	v_rcp_f32_e32 v193, v193
	v_pk_mul_f32 v[94:95], v[94:95], v[188:189] op_sel_hi:[1,0]
	v_pk_mul_f32 v[92:93], v[92:93], v[190:191]
	v_pk_mul_f32 v[94:95], v[94:95], v[192:193]
	v_pk_mul_f32 v[190:191], v[84:85], v[186:187] op_sel_hi:[1,0]
	v_pk_mul_f32 v[192:193], v[86:87], v[186:187] op_sel_hi:[1,0]
	v_pk_mul_f32 v[84:85], v[84:85], v[80:81]
	v_exp_f32_e32 v190, v190
	v_exp_f32_e32 v191, v191
	v_exp_f32_e32 v192, v192
	v_exp_f32_e32 v193, v193
	v_pk_mul_f32 v[86:87], v[86:87], v[82:83]
	v_pk_add_f32 v[190:191], v[190:191], v[182:183] op_sel_hi:[1,0]
	v_pk_add_f32 v[192:193], v[192:193], v[182:183] op_sel_hi:[1,0]
	v_pk_mul_f32 v[84:85], v[84:85], v[188:189] op_sel_hi:[1,0]
	v_rcp_f32_e32 v190, v190
	v_rcp_f32_e32 v191, v191
	v_rcp_f32_e32 v192, v192
	v_rcp_f32_e32 v193, v193
	v_pk_mul_f32 v[86:87], v[86:87], v[188:189] op_sel_hi:[1,0]
	v_pk_mul_f32 v[84:85], v[84:85], v[190:191]
	v_pk_mul_f32 v[86:87], v[86:87], v[192:193]
	v_cvt_pk_bf16_f32 v194, v92, v93
	v_cvt_pk_bf16_f32 v195, v94, v95
	v_cvt_pk_bf16_f32 v196, v84, v85
	v_cvt_pk_bf16_f32 v197, v86, v87
	global_store_dwordx4 v[202:203], v[194:197], off offset:0
	v_fmamk_f32 v184, v175, 0x3a000000, v145
	v_rsq_f32_e32 v184, v184
	s_nop 0
	v_mul_f32_e32 v184, 0x3a800000, v184
	v_mul_f32_e32 v186, 0xbfb8aa3b, v184
	v_mul_f32_e32 v188, v184, v184
	v_pk_mul_f32 v[190:191], v[76:77], v[186:187] op_sel_hi:[1,0]
	v_pk_mul_f32 v[192:193], v[78:79], v[186:187] op_sel_hi:[1,0]
	v_pk_mul_f32 v[76:77], v[76:77], v[72:73]
	v_exp_f32_e32 v190, v190
	v_exp_f32_e32 v191, v191
	v_exp_f32_e32 v192, v192
	v_exp_f32_e32 v193, v193
	v_pk_mul_f32 v[78:79], v[78:79], v[74:75]
	v_pk_add_f32 v[190:191], v[190:191], v[182:183] op_sel_hi:[1,0]
	v_pk_add_f32 v[192:193], v[192:193], v[182:183] op_sel_hi:[1,0]
	v_pk_mul_f32 v[76:77], v[76:77], v[188:189] op_sel_hi:[1,0]
	v_rcp_f32_e32 v190, v190
	v_rcp_f32_e32 v191, v191
	v_rcp_f32_e32 v192, v192
	v_rcp_f32_e32 v193, v193
	v_pk_mul_f32 v[78:79], v[78:79], v[188:189] op_sel_hi:[1,0]
	v_pk_mul_f32 v[76:77], v[76:77], v[190:191]
	v_pk_mul_f32 v[78:79], v[78:79], v[192:193]
	v_pk_mul_f32 v[190:191], v[68:69], v[186:187] op_sel_hi:[1,0]
	v_pk_mul_f32 v[192:193], v[70:71], v[186:187] op_sel_hi:[1,0]
	v_pk_mul_f32 v[68:69], v[68:69], v[64:65]
	v_exp_f32_e32 v190, v190
	v_exp_f32_e32 v191, v191
	v_exp_f32_e32 v192, v192
	v_exp_f32_e32 v193, v193
	v_pk_mul_f32 v[70:71], v[70:71], v[66:67]
	v_pk_add_f32 v[190:191], v[190:191], v[182:183] op_sel_hi:[1,0]
	v_pk_add_f32 v[192:193], v[192:193], v[182:183] op_sel_hi:[1,0]
	v_pk_mul_f32 v[68:69], v[68:69], v[188:189] op_sel_hi:[1,0]
	v_rcp_f32_e32 v190, v190
	v_rcp_f32_e32 v191, v191
	v_rcp_f32_e32 v192, v192
	v_rcp_f32_e32 v193, v193
	v_pk_mul_f32 v[70:71], v[70:71], v[188:189] op_sel_hi:[1,0]
	v_pk_mul_f32 v[68:69], v[68:69], v[190:191]
	v_pk_mul_f32 v[70:71], v[70:71], v[192:193]
	v_cvt_pk_bf16_f32 v198, v76, v77
	v_cvt_pk_bf16_f32 v199, v78, v79
	v_cvt_pk_bf16_f32 v200, v68, v69
	v_cvt_pk_bf16_f32 v201, v70, v71
	global_store_dwordx4 v[202:203], v[198:201], off offset:2048
	v_fmamk_f32 v184, v176, 0x3a000000, v145
	v_rsq_f32_e32 v184, v184
	s_nop 0
	v_mul_f32_e32 v184, 0x3a800000, v184
	v_mul_f32_e32 v186, 0xbfb8aa3b, v184
	v_mul_f32_e32 v188, v184, v184
	v_pk_mul_f32 v[190:191], v[60:61], v[186:187] op_sel_hi:[1,0]
	v_pk_mul_f32 v[192:193], v[62:63], v[186:187] op_sel_hi:[1,0]
	v_pk_mul_f32 v[60:61], v[60:61], v[56:57]
	v_exp_f32_e32 v190, v190
	v_exp_f32_e32 v191, v191
	v_exp_f32_e32 v192, v192
	v_exp_f32_e32 v193, v193
	v_pk_mul_f32 v[62:63], v[62:63], v[58:59]
	v_pk_add_f32 v[190:191], v[190:191], v[182:183] op_sel_hi:[1,0]
	v_pk_add_f32 v[192:193], v[192:193], v[182:183] op_sel_hi:[1,0]
	v_pk_mul_f32 v[60:61], v[60:61], v[188:189] op_sel_hi:[1,0]
	v_rcp_f32_e32 v190, v190
	v_rcp_f32_e32 v191, v191
	v_rcp_f32_e32 v192, v192
	v_rcp_f32_e32 v193, v193
	v_pk_mul_f32 v[62:63], v[62:63], v[188:189] op_sel_hi:[1,0]
	v_pk_mul_f32 v[60:61], v[60:61], v[190:191]
	v_pk_mul_f32 v[62:63], v[62:63], v[192:193]
	v_pk_mul_f32 v[190:191], v[52:53], v[186:187] op_sel_hi:[1,0]
	v_pk_mul_f32 v[192:193], v[54:55], v[186:187] op_sel_hi:[1,0]
	v_pk_mul_f32 v[52:53], v[52:53], v[48:49]
	v_exp_f32_e32 v190, v190
	v_exp_f32_e32 v191, v191
	v_exp_f32_e32 v192, v192
	v_exp_f32_e32 v193, v193
	v_pk_mul_f32 v[54:55], v[54:55], v[50:51]
	v_pk_add_f32 v[190:191], v[190:191], v[182:183] op_sel_hi:[1,0]
	v_pk_add_f32 v[192:193], v[192:193], v[182:183] op_sel_hi:[1,0]
	v_pk_mul_f32 v[52:53], v[52:53], v[188:189] op_sel_hi:[1,0]
	v_rcp_f32_e32 v190, v190
	v_rcp_f32_e32 v191, v191
	v_rcp_f32_e32 v192, v192
	v_rcp_f32_e32 v193, v193
	v_pk_mul_f32 v[54:55], v[54:55], v[188:189] op_sel_hi:[1,0]
	v_pk_mul_f32 v[52:53], v[52:53], v[190:191]
	v_pk_mul_f32 v[54:55], v[54:55], v[192:193]
	v_cvt_pk_bf16_f32 v194, v60, v61
	v_cvt_pk_bf16_f32 v195, v62, v63
	v_cvt_pk_bf16_f32 v196, v52, v53
; __device__ __forceinline__ float rstd_of(float ss, float inv_n) { return __builtin_amdgcn_rsqf(ss * inv_n + 1e-6f); }
; #define PG8_BAR __builtin_amdgcn_s_barrier()
;     __device__ __forceinline__ void operator()(f32x4 (&acc)[2][2][4][2], const Unit& u_, int wr, int wc, int fr, int fq) const {
;     ...
;             for (int m = 0; m < 4; ++m) {
;                 const int row = row0 + ai * HALF + m * 16; const float r = rstd_of(sl[u.par * 256 + ai * HALF + wr * 64 + m * 16 + fr], 1.0f / 2048.0f) * ascale;
;                 f32x4 o[2];
; #pragma unroll
;                 for (int n = 0; n < 2; ++n) { const f32x4 g = acc[ai][0][m][n] * r, uu = acc[ai][1][m][n] * r;
; #pragma unroll
;                     for (int e = 0; e < 4; ++e) o[n][e] = g[e] * uu[e] * sigmoid_f(g[e]); }
;                 if constexpr (F8OUT) {
;                     typedef unsigned u32x2 __attribute__((ext_vector_type(2))); u32x2 w8; w8.x = pack4_fp8(o[0][0] * F8_ACT_SCALE, o[0][1] * F8_ACT_SCALE, o[0][2] * F8_ACT_SCALE, o[0][3] * F8_ACT_SCALE);
;                     w8.y = pack4_fp8(o[1][0] * F8_ACT_SCALE, o[1][1] * F8_ACT_SCALE, o[1][2] * F8_ACT_SCALE, o[1][3] * F8_ACT_SCALE);
;                     *(u32x2*)((unsigned char*)O + (((size_t)u.pm * (ldo / 128) + (col0 >> 7)) * BM + (ai * HALF + wr * 64 + m * 16 + fr)) * 128 + (col0 & 127)) = w8;
;                 } else
;                 *(u32x4*)(O + (((size_t)u.pm * (ldo / 64) + (col0 >> 6)) * BM + (ai * HALF + wr * 64 + m * 16 + fr)) * 64 + (col0 & 63)) = pack8(o[0], o[1]);
; template <class Epi, class Sched, bool ALIGN_EPI = false, bool SP2 = false, bool ABLK = false, bool F8 = false>
; __device__ __forceinline__ void gemm_phase(PG8_LAS unsigned char* lds, const Gemm g, const Sched& S, const Epi& E, const int wave_s) {
;     ...
;         if constexpr (!Epi::AFTER_DRAIN) { E(acc, cur, wr, wc, fr, fq); S.done(cur); }
;         if (!has_next) break;
;         if (!(Epi::MID && cur.kh == 0))
; #pragma unroll
;         for (int a = 0; a < 2; ++a)
; #pragma unroll
;             for (int b = 0; b < 2; ++b)
; #pragma unroll
;                 for (int m = 0; m < 4; ++m)
; #pragma unroll
;                     for (int n = 0; n < 2; ++n) acc[a][b][m][n] = (f32x4){0.f, 0.f, 0.f, 0.f};
;         cur = nxt; cA = nA; cB = nB; ++ui;
;         if constexpr (ALIGN_EPI) { if (wr == 1) PG8_BAR; }
	v_cvt_pk_bf16_f32 v197, v54, v55
	global_store_dwordx4 v[204:205], v[194:197], off offset:-4096
	v_fmamk_f32 v184, v177, 0x3a000000, v145
	v_rsq_f32_e32 v184, v184
	s_nop 0
	v_mul_f32_e32 v184, 0x3a800000, v184
	v_mul_f32_e32 v186, 0xbfb8aa3b, v184
	v_mul_f32_e32 v188, v184, v184
	v_pk_mul_f32 v[190:191], v[44:45], v[186:187] op_sel_hi:[1,0]
	v_pk_mul_f32 v[192:193], v[46:47], v[186:187] op_sel_hi:[1,0]
	v_pk_mul_f32 v[44:45], v[44:45], v[40:41]
	v_exp_f32_e32 v190, v190
	v_exp_f32_e32 v191, v191
	v_exp_f32_e32 v192, v192
	v_exp_f32_e32 v193, v193
	v_pk_mul_f32 v[46:47], v[46:47], v[42:43]
	v_pk_add_f32 v[190:191], v[190:191], v[182:183] op_sel_hi:[1,0]
	v_pk_add_f32 v[192:193], v[192:193], v[182:183] op_sel_hi:[1,0]
	v_pk_mul_f32 v[44:45], v[44:45], v[188:189] op_sel_hi:[1,0]
	v_rcp_f32_e32 v190, v190
	v_rcp_f32_e32 v191, v191
	v_rcp_f32_e32 v192, v192
	v_rcp_f32_e32 v193, v193
	v_pk_mul_f32 v[46:47], v[46:47], v[188:189] op_sel_hi:[1,0]
	v_pk_mul_f32 v[44:45], v[44:45], v[190:191]
	v_pk_mul_f32 v[46:47], v[46:47], v[192:193]
	v_pk_mul_f32 v[190:191], v[36:37], v[186:187] op_sel_hi:[1,0]
	v_pk_mul_f32 v[192:193], v[38:39], v[186:187] op_sel_hi:[1,0]
	v_pk_mul_f32 v[36:37], v[36:37], v[32:33]
	v_exp_f32_e32 v190, v190
	v_exp_f32_e32 v191, v191
	v_exp_f32_e32 v192, v192
	v_exp_f32_e32 v193, v193
	v_pk_mul_f32 v[38:39], v[38:39], v[34:35]
	v_pk_add_f32 v[190:191], v[190:191], v[182:183] op_sel_hi:[1,0]
	v_pk_add_f32 v[192:193], v[192:193], v[182:183] op_sel_hi:[1,0]
	v_pk_mul_f32 v[36:37], v[36:37], v[188:189] op_sel_hi:[1,0]
	v_rcp_f32_e32 v190, v190
	v_rcp_f32_e32 v191, v191
	v_rcp_f32_e32 v192, v192
	v_rcp_f32_e32 v193, v193
	v_pk_mul_f32 v[38:39], v[38:39], v[188:189] op_sel_hi:[1,0]
	v_pk_mul_f32 v[36:37], v[36:37], v[190:191]
	v_pk_mul_f32 v[38:39], v[38:39], v[192:193]
	v_cvt_pk_bf16_f32 v198, v44, v45
	v_cvt_pk_bf16_f32 v199, v46, v47
	v_cvt_pk_bf16_f32 v200, v36, v37
	v_cvt_pk_bf16_f32 v201, v38, v39
	global_store_dwordx4 v[204:205], v[198:201], off offset:-2048
	v_fmamk_f32 v184, v178, 0x3a000000, v145
	v_rsq_f32_e32 v184, v184
	s_nop 0
	v_mul_f32_e32 v184, 0x3a800000, v184
	v_mul_f32_e32 v186, 0xbfb8aa3b, v184
	v_mul_f32_e32 v188, v184, v184
	v_pk_mul_f32 v[190:191], v[28:29], v[186:187] op_sel_hi:[1,0]
	v_pk_mul_f32 v[192:193], v[30:31], v[186:187] op_sel_hi:[1,0]
	v_pk_mul_f32 v[28:29], v[28:29], v[24:25]
	v_exp_f32_e32 v190, v190
	v_exp_f32_e32 v191, v191
	v_exp_f32_e32 v192, v192
	v_exp_f32_e32 v193, v193
	v_pk_mul_f32 v[30:31], v[30:31], v[26:27]
	v_pk_add_f32 v[190:191], v[190:191], v[182:183] op_sel_hi:[1,0]
	v_pk_add_f32 v[192:193], v[192:193], v[182:183] op_sel_hi:[1,0]
	v_pk_mul_f32 v[28:29], v[28:29], v[188:189] op_sel_hi:[1,0]
	v_rcp_f32_e32 v190, v190
	v_rcp_f32_e32 v191, v191
	v_rcp_f32_e32 v192, v192
	v_rcp_f32_e32 v193, v193
	v_pk_mul_f32 v[30:31], v[30:31], v[188:189] op_sel_hi:[1,0]
	v_pk_mul_f32 v[28:29], v[28:29], v[190:191]
	v_pk_mul_f32 v[30:31], v[30:31], v[192:193]
	v_pk_mul_f32 v[190:191], v[20:21], v[186:187] op_sel_hi:[1,0]
	v_pk_mul_f32 v[192:193], v[22:23], v[186:187] op_sel_hi:[1,0]
	v_pk_mul_f32 v[20:21], v[20:21], v[16:17]
	v_exp_f32_e32 v190, v190
	v_exp_f32_e32 v191, v191
	v_exp_f32_e32 v192, v192
	v_exp_f32_e32 v193, v193
	v_pk_mul_f32 v[22:23], v[22:23], v[18:19]
	v_pk_add_f32 v[190:191], v[190:191], v[182:183] op_sel_hi:[1,0]
	v_pk_add_f32 v[192:193], v[192:193], v[182:183] op_sel_hi:[1,0]
	v_pk_mul_f32 v[20:21], v[20:21], v[188:189] op_sel_hi:[1,0]
	v_rcp_f32_e32 v190, v190
	v_rcp_f32_e32 v191, v191
	v_rcp_f32_e32 v192, v192
	v_rcp_f32_e32 v193, v193
	v_pk_mul_f32 v[22:23], v[22:23], v[188:189] op_sel_hi:[1,0]
	v_pk_mul_f32 v[20:21], v[20:21], v[190:191]
	v_pk_mul_f32 v[22:23], v[22:23], v[192:193]
	v_cvt_pk_bf16_f32 v194, v28, v29
	v_cvt_pk_bf16_f32 v195, v30, v31
	v_cvt_pk_bf16_f32 v196, v20, v21
	v_cvt_pk_bf16_f32 v197, v22, v23
	global_store_dwordx4 v[204:205], v[194:197], off offset:0
	v_fmamk_f32 v184, v179, 0x3a000000, v145
	v_rsq_f32_e32 v184, v184
	s_nop 0
	v_mul_f32_e32 v184, 0x3a800000, v184
	v_mul_f32_e32 v186, 0xbfb8aa3b, v184
	v_mul_f32_e32 v188, v184, v184
	v_pk_mul_f32 v[190:191], v[12:13], v[186:187] op_sel_hi:[1,0]
	v_pk_mul_f32 v[192:193], v[14:15], v[186:187] op_sel_hi:[1,0]
	v_pk_mul_f32 v[12:13], v[12:13], v[8:9]
	v_exp_f32_e32 v190, v190
	v_exp_f32_e32 v191, v191
	v_exp_f32_e32 v192, v192
	v_exp_f32_e32 v193, v193
	v_pk_mul_f32 v[14:15], v[14:15], v[10:11]
	v_pk_add_f32 v[190:191], v[190:191], v[182:183] op_sel_hi:[1,0]
	v_pk_add_f32 v[192:193], v[192:193], v[182:183] op_sel_hi:[1,0]
	v_pk_mul_f32 v[12:13], v[12:13], v[188:189] op_sel_hi:[1,0]
	v_rcp_f32_e32 v190, v190
	v_rcp_f32_e32 v191, v191
	v_rcp_f32_e32 v192, v192
	v_rcp_f32_e32 v193, v193
	v_pk_mul_f32 v[14:15], v[14:15], v[188:189] op_sel_hi:[1,0]
	v_pk_mul_f32 v[12:13], v[12:13], v[190:191]
	v_pk_mul_f32 v[14:15], v[14:15], v[192:193]
	v_pk_mul_f32 v[190:191], v[4:5], v[186:187] op_sel_hi:[1,0]
	v_pk_mul_f32 v[192:193], v[6:7], v[186:187] op_sel_hi:[1,0]
	v_pk_mul_f32 v[4:5], v[4:5], v[0:1]
	v_exp_f32_e32 v190, v190
	v_exp_f32_e32 v191, v191
	v_exp_f32_e32 v192, v192
	v_exp_f32_e32 v193, v193
	v_pk_mul_f32 v[6:7], v[6:7], v[2:3]
	v_pk_add_f32 v[190:191], v[190:191], v[182:183] op_sel_hi:[1,0]
	v_pk_add_f32 v[192:193], v[192:193], v[182:183] op_sel_hi:[1,0]
	v_pk_mul_f32 v[4:5], v[4:5], v[188:189] op_sel_hi:[1,0]
	v_rcp_f32_e32 v190, v190
	v_rcp_f32_e32 v191, v191
	v_rcp_f32_e32 v192, v192
	v_rcp_f32_e32 v193, v193
	v_pk_mul_f32 v[6:7], v[6:7], v[188:189] op_sel_hi:[1,0]
	v_pk_mul_f32 v[4:5], v[4:5], v[190:191]
	v_pk_mul_f32 v[6:7], v[6:7], v[192:193]
	v_cvt_pk_bf16_f32 v198, v12, v13
	v_cvt_pk_bf16_f32 v199, v14, v15
	v_cvt_pk_bf16_f32 v200, v4, v5
	v_cvt_pk_bf16_f32 v201, v6, v7
	global_store_dwordx4 v[204:205], v[198:201], off offset:2048
	s_cbranch_vccnz .LBB0_806
	s_and_b64 vcc, exec, s[16:17]
	s_cbranch_vccnz .LBB0_805
	s_barrier
	s_branch .LBB0_805
